# P15 row pass: blocked row assignment (workgroup owns 34 consecutive rows) instead of rows gw + 2048 i
# speedup vs baseline: 1.0093x; 1.0093x over previous
.LBB0_1602:
	s_cmp_lt_i32 s72, 16
	s_cselect_b64 s[2:3], -1, 0
	s_and_b64 s[0:1], s[2:3], s[0:1]
	s_andn2_b64 vcc, exec, s[0:1]
	s_cbranch_vccnz .LBB0_1608
	s_cmpk_gt_i32 s96, 0x21ff
	s_cbranch_scc1 .LBB0_1608
	v_readlane_b32 s0, v242, 12
	v_readlane_b32 s1, v242, 13
	v_readlane_b32 s6, v242, 51
	v_readlane_b32 s7, v242, 52
	v_lshlrev_b32_e32 v252, 3, v142
	v_lshlrev_b32_e32 v253, 4, v142
	v_add_u32_e32 v254, 0x1000, v253
	v_mov_b32_e32 v255, 0x358637bd
	v_xor_b32_e32 v128, 1, v142
	v_lshlrev_b32_e32 v244, 2, v128
	v_xor_b32_e32 v128, 2, v142
	v_lshlrev_b32_e32 v245, 2, v128
	v_xor_b32_e32 v128, 4, v142
	v_lshlrev_b32_e32 v246, 2, v128
	v_xor_b32_e32 v128, 8, v142
	v_lshlrev_b32_e32 v247, 2, v128
	v_xor_b32_e32 v128, 16, v142
	v_lshlrev_b32_e32 v248, 2, v128
	v_xor_b32_e32 v128, 32, v142
	v_lshlrev_b32_e32 v249, 2, v128
	s_add_u32 s0, s0, 0x2000
	s_addc_u32 s1, s1, 0
	global_load_dwordx4 v[0:3], v253, s[0:1] offset:0
	global_load_dwordx4 v[4:7], v253, s[0:1] offset:1024
	global_load_dwordx4 v[8:11], v253, s[0:1] offset:2048
	global_load_dwordx4 v[12:15], v253, s[0:1] offset:3072
	global_load_dwordx4 v[16:19], v254, s[0:1] offset:0
	global_load_dwordx4 v[20:23], v254, s[0:1] offset:1024
	global_load_dwordx4 v[24:27], v254, s[0:1] offset:2048
	global_load_dwordx4 v[28:31], v254, s[0:1] offset:3072
	s_lshr_b32 s8, s96, 3
	s_mul_i32 s8, s8, 34
	s_and_b32 s9, s96, 7
	s_add_u32 s8, s8, s9
	s_mov_b32 s9, 0
	s_and_b32 s11, s96, 7
	s_lshl_b64 s[4:5], s[8:9], 12
	s_add_u32 s0, s6, s4
	s_addc_u32 s1, s7, s5
	s_add_u32 s2, s40, s4
	s_addc_u32 s3, s41, s5
	global_load_dwordx2 v[32:33], v252, s[0:1] offset:0
	global_load_dwordx2 v[34:35], v252, s[0:1] offset:512
	global_load_dwordx2 v[36:37], v252, s[0:1] offset:1024
	global_load_dwordx2 v[38:39], v252, s[0:1] offset:1536
	global_load_dwordx2 v[40:41], v252, s[0:1] offset:2048
	global_load_dwordx2 v[42:43], v252, s[0:1] offset:2560
	global_load_dwordx2 v[44:45], v252, s[0:1] offset:3072
	global_load_dwordx2 v[46:47], v252, s[0:1] offset:3584
	global_load_dwordx2 v[48:49], v252, s[2:3] offset:0
	global_load_dwordx2 v[50:51], v252, s[2:3] offset:512
	global_load_dwordx2 v[52:53], v252, s[2:3] offset:1024
	global_load_dwordx2 v[54:55], v252, s[2:3] offset:1536
	global_load_dwordx2 v[56:57], v252, s[2:3] offset:2048
	global_load_dwordx2 v[58:59], v252, s[2:3] offset:2560
	global_load_dwordx2 v[60:61], v252, s[2:3] offset:3072
	global_load_dwordx2 v[62:63], v252, s[2:3] offset:3584
	s_add_u32 s0, s0, 0x8000
	s_addc_u32 s1, s1, 0
	s_add_u32 s2, s2, 0x8000
	s_addc_u32 s3, s3, 0
	global_load_dwordx2 v[64:65], v252, s[0:1] offset:0
	global_load_dwordx2 v[66:67], v252, s[0:1] offset:512
	global_load_dwordx2 v[68:69], v252, s[0:1] offset:1024
	global_load_dwordx2 v[70:71], v252, s[0:1] offset:1536
	global_load_dwordx2 v[72:73], v252, s[0:1] offset:2048
	global_load_dwordx2 v[74:75], v252, s[0:1] offset:2560
	global_load_dwordx2 v[76:77], v252, s[0:1] offset:3072
	global_load_dwordx2 v[78:79], v252, s[0:1] offset:3584
	global_load_dwordx2 v[80:81], v252, s[2:3] offset:0
	global_load_dwordx2 v[82:83], v252, s[2:3] offset:512
	global_load_dwordx2 v[84:85], v252, s[2:3] offset:1024
	global_load_dwordx2 v[86:87], v252, s[2:3] offset:1536
	global_load_dwordx2 v[88:89], v252, s[2:3] offset:2048
	global_load_dwordx2 v[90:91], v252, s[2:3] offset:2560
	global_load_dwordx2 v[92:93], v252, s[2:3] offset:3072
	global_load_dwordx2 v[94:95], v252, s[2:3] offset:3584
	s_add_u32 s0, s0, 0x8000
	s_addc_u32 s1, s1, 0
	s_add_u32 s2, s2, 0x8000
	s_addc_u32 s3, s3, 0
	global_load_dwordx2 v[96:97], v252, s[0:1] offset:0
	global_load_dwordx2 v[98:99], v252, s[0:1] offset:512
	global_load_dwordx2 v[100:101], v252, s[0:1] offset:1024
	global_load_dwordx2 v[102:103], v252, s[0:1] offset:1536
	global_load_dwordx2 v[104:105], v252, s[0:1] offset:2048
	global_load_dwordx2 v[106:107], v252, s[0:1] offset:2560
	global_load_dwordx2 v[108:109], v252, s[0:1] offset:3072
	global_load_dwordx2 v[110:111], v252, s[0:1] offset:3584
	global_load_dwordx2 v[112:113], v252, s[2:3] offset:0
	global_load_dwordx2 v[114:115], v252, s[2:3] offset:512
	global_load_dwordx2 v[116:117], v252, s[2:3] offset:1024
	global_load_dwordx2 v[118:119], v252, s[2:3] offset:1536
	global_load_dwordx2 v[120:121], v252, s[2:3] offset:2048
	global_load_dwordx2 v[122:123], v252, s[2:3] offset:2560
	global_load_dwordx2 v[124:125], v252, s[2:3] offset:3072
	global_load_dwordx2 v[126:127], v252, s[2:3] offset:3584
	s_add_u32 s0, s0, 0x8000
	s_addc_u32 s1, s1, 0
	s_add_u32 s2, s2, 0x8000
	s_addc_u32 s3, s3, 0
	s_lshl_b64 s[4:5], s[8:9], 13
	s_add_u32 s4, s68, s4
	s_addc_u32 s5, s69, s5
	v_mov_b32_e32 v250, v253
	v_mov_b32_e32 v251, 0
	v_lshl_add_u64 v[250:251], s[4:5], 0, v[250:251]
	s_mov_b64 s[12:13], 0x10000
	s_mov_b64 s[14:15], 0x1000
	s_mov_b32 s10, 0x800000
	s_waitcnt vmcnt(32)
	v_lshlrev_b32_e32 v208, 16, v48
	v_and_b32_e32 v209, 0xffff0000, v48
	v_lshlrev_b32_e32 v210, 16, v49
	v_and_b32_e32 v211, 0xffff0000, v49
	v_lshlrev_b32_e32 v212, 16, v50
	v_and_b32_e32 v213, 0xffff0000, v50
	v_lshlrev_b32_e32 v214, 16, v51
	v_and_b32_e32 v215, 0xffff0000, v51
	v_lshlrev_b32_e32 v216, 16, v52
	v_and_b32_e32 v217, 0xffff0000, v52
	v_lshlrev_b32_e32 v218, 16, v53
	v_and_b32_e32 v219, 0xffff0000, v53
	v_lshlrev_b32_e32 v220, 16, v54
	v_and_b32_e32 v221, 0xffff0000, v54
	v_lshlrev_b32_e32 v222, 16, v55
	v_and_b32_e32 v223, 0xffff0000, v55
	v_lshlrev_b32_e32 v224, 16, v56
	v_and_b32_e32 v225, 0xffff0000, v56
	v_lshlrev_b32_e32 v226, 16, v57
	v_and_b32_e32 v227, 0xffff0000, v57
	v_lshlrev_b32_e32 v228, 16, v58
	v_and_b32_e32 v229, 0xffff0000, v58
	v_lshlrev_b32_e32 v230, 16, v59
	v_and_b32_e32 v231, 0xffff0000, v59
	v_lshlrev_b32_e32 v232, 16, v60
	v_and_b32_e32 v233, 0xffff0000, v60
	v_lshlrev_b32_e32 v234, 16, v61
	v_and_b32_e32 v235, 0xffff0000, v61
	v_lshlrev_b32_e32 v236, 16, v62
	v_and_b32_e32 v237, 0xffff0000, v62
	v_lshlrev_b32_e32 v238, 16, v63
	v_and_b32_e32 v239, 0xffff0000, v63
	v_mul_f32_e32 v128, v208, v208
	v_fmac_f32_e32 v128, v209, v209
	v_mul_f32_e32 v129, v210, v210
	v_fmac_f32_e32 v129, v211, v211
	v_add_f32_e32 v128, v128, v129
	v_mul_f32_e32 v129, v212, v212
	v_fmac_f32_e32 v129, v213, v213
	v_mul_f32_e32 v132, v214, v214
	v_fmac_f32_e32 v132, v215, v215
	v_add_f32_e32 v129, v129, v132
	v_add_f32_e32 v128, v128, v129
	v_mul_f32_e32 v129, v216, v216
	v_fmac_f32_e32 v129, v217, v217
	v_mul_f32_e32 v132, v218, v218
	v_fmac_f32_e32 v132, v219, v219
	v_add_f32_e32 v129, v129, v132
	v_add_f32_e32 v128, v128, v129
	v_mul_f32_e32 v129, v220, v220
	v_fmac_f32_e32 v129, v221, v221
	v_mul_f32_e32 v132, v222, v222
	v_fmac_f32_e32 v132, v223, v223
	v_add_f32_e32 v129, v129, v132
	v_add_f32_e32 v128, v128, v129
	v_mul_f32_e32 v129, v224, v224
	v_fmac_f32_e32 v129, v225, v225
	v_mul_f32_e32 v132, v226, v226
	v_fmac_f32_e32 v132, v227, v227
	v_add_f32_e32 v129, v129, v132
	v_add_f32_e32 v128, v128, v129
	v_mul_f32_e32 v129, v228, v228
	v_fmac_f32_e32 v129, v229, v229
	v_mul_f32_e32 v132, v230, v230
	v_fmac_f32_e32 v132, v231, v231
	v_add_f32_e32 v129, v129, v132
	v_add_f32_e32 v128, v128, v129
	v_mul_f32_e32 v129, v232, v232
	v_fmac_f32_e32 v129, v233, v233
	v_mul_f32_e32 v132, v234, v234
	v_fmac_f32_e32 v132, v235, v235
	v_add_f32_e32 v129, v129, v132
	v_add_f32_e32 v128, v128, v129
	v_mul_f32_e32 v129, v236, v236
	v_fmac_f32_e32 v129, v237, v237
	v_mul_f32_e32 v132, v238, v238
	v_fmac_f32_e32 v132, v239, v239
	v_add_f32_e32 v129, v129, v132
	v_add_f32_e32 v128, v128, v129
	ds_bpermute_b32 v129, v244, v128
	s_waitcnt lgkmcnt(0)
	v_add_f32_e32 v128, v128, v129
	ds_bpermute_b32 v129, v245, v128
	s_waitcnt lgkmcnt(0)
	v_add_f32_e32 v128, v128, v129
	ds_bpermute_b32 v129, v246, v128
	s_waitcnt lgkmcnt(0)
	v_add_f32_e32 v128, v128, v129
	ds_bpermute_b32 v129, v247, v128
	s_waitcnt lgkmcnt(0)
	v_add_f32_e32 v128, v128, v129
	ds_bpermute_b32 v129, v248, v128
	s_waitcnt lgkmcnt(0)
	v_add_f32_e32 v128, v128, v129
	ds_bpermute_b32 v129, v249, v128
	s_waitcnt lgkmcnt(0)
	v_add_f32_e32 v128, v128, v129
	v_fmamk_f32 v128, v128, 0x3a000000, v255
	v_mul_f32_e32 v129, 0x4b800000, v128
	v_cmp_gt_f32_e32 vcc, s10, v128
	s_nop 1
	v_cndmask_b32_e32 v128, v128, v129, vcc
	v_rsq_f32_e32 v128, v128
	s_nop 0
	v_mul_f32_e32 v129, 0x45800000, v128
	v_cndmask_b32_e32 v130, v128, v129, vcc
	v_lshl_add_u64 v[140:141], v[250:251], 0, s[14:15]
	v_lshlrev_b32_e32 v136, 16, v32
	v_and_b32_e32 v137, 0xffff0000, v32
	v_lshlrev_b32_e32 v138, 16, v33
	v_and_b32_e32 v139, 0xffff0000, v33
	v_pk_mul_f32 v[208:209], v[130:131], v[208:209] op_sel_hi:[0,1]
	v_pk_fma_f32 v[208:209], v[0:1], v[208:209], v[136:137]
	v_pk_mul_f32 v[210:211], v[130:131], v[210:211] op_sel_hi:[0,1]
	v_pk_fma_f32 v[210:211], v[2:3], v[210:211], v[138:139]
	global_store_dwordx4 v[250:251], v[208:211], off offset:0
	v_lshlrev_b32_e32 v136, 16, v34
	v_and_b32_e32 v137, 0xffff0000, v34
	v_lshlrev_b32_e32 v138, 16, v35
	v_and_b32_e32 v139, 0xffff0000, v35
	v_pk_mul_f32 v[212:213], v[130:131], v[212:213] op_sel_hi:[0,1]
	v_pk_fma_f32 v[212:213], v[4:5], v[212:213], v[136:137]
	v_pk_mul_f32 v[214:215], v[130:131], v[214:215] op_sel_hi:[0,1]
	v_pk_fma_f32 v[214:215], v[6:7], v[214:215], v[138:139]
	global_store_dwordx4 v[250:251], v[212:215], off offset:1024
	v_lshlrev_b32_e32 v136, 16, v36
	v_and_b32_e32 v137, 0xffff0000, v36
	v_lshlrev_b32_e32 v138, 16, v37
	v_and_b32_e32 v139, 0xffff0000, v37
	v_pk_mul_f32 v[216:217], v[130:131], v[216:217] op_sel_hi:[0,1]
	v_pk_fma_f32 v[216:217], v[8:9], v[216:217], v[136:137]
	v_pk_mul_f32 v[218:219], v[130:131], v[218:219] op_sel_hi:[0,1]
	v_pk_fma_f32 v[218:219], v[10:11], v[218:219], v[138:139]
	global_store_dwordx4 v[250:251], v[216:219], off offset:2048
	v_lshlrev_b32_e32 v136, 16, v38
	v_and_b32_e32 v137, 0xffff0000, v38
	v_lshlrev_b32_e32 v138, 16, v39
	v_and_b32_e32 v139, 0xffff0000, v39
	v_pk_mul_f32 v[220:221], v[130:131], v[220:221] op_sel_hi:[0,1]
	v_pk_fma_f32 v[220:221], v[12:13], v[220:221], v[136:137]
	v_pk_mul_f32 v[222:223], v[130:131], v[222:223] op_sel_hi:[0,1]
	v_pk_fma_f32 v[222:223], v[14:15], v[222:223], v[138:139]
	global_store_dwordx4 v[250:251], v[220:223], off offset:3072
	v_lshlrev_b32_e32 v136, 16, v40
	v_and_b32_e32 v137, 0xffff0000, v40
	v_lshlrev_b32_e32 v138, 16, v41
	v_and_b32_e32 v139, 0xffff0000, v41
	v_pk_mul_f32 v[224:225], v[130:131], v[224:225] op_sel_hi:[0,1]
	v_pk_fma_f32 v[224:225], v[16:17], v[224:225], v[136:137]
	v_pk_mul_f32 v[226:227], v[130:131], v[226:227] op_sel_hi:[0,1]
	v_pk_fma_f32 v[226:227], v[18:19], v[226:227], v[138:139]
	global_store_dwordx4 v[140:141], v[224:227], off offset:0
	v_lshlrev_b32_e32 v136, 16, v42
	v_and_b32_e32 v137, 0xffff0000, v42
	v_lshlrev_b32_e32 v138, 16, v43
	v_and_b32_e32 v139, 0xffff0000, v43
	v_pk_mul_f32 v[228:229], v[130:131], v[228:229] op_sel_hi:[0,1]
	v_pk_fma_f32 v[228:229], v[20:21], v[228:229], v[136:137]
	v_pk_mul_f32 v[230:231], v[130:131], v[230:231] op_sel_hi:[0,1]
	v_pk_fma_f32 v[230:231], v[22:23], v[230:231], v[138:139]
	global_store_dwordx4 v[140:141], v[228:231], off offset:1024
	v_lshlrev_b32_e32 v136, 16, v44
	v_and_b32_e32 v137, 0xffff0000, v44
	v_lshlrev_b32_e32 v138, 16, v45
	v_and_b32_e32 v139, 0xffff0000, v45
	v_pk_mul_f32 v[232:233], v[130:131], v[232:233] op_sel_hi:[0,1]
	v_pk_fma_f32 v[232:233], v[24:25], v[232:233], v[136:137]
	v_pk_mul_f32 v[234:235], v[130:131], v[234:235] op_sel_hi:[0,1]
	v_pk_fma_f32 v[234:235], v[26:27], v[234:235], v[138:139]
	global_store_dwordx4 v[140:141], v[232:235], off offset:2048
	v_lshlrev_b32_e32 v136, 16, v46
	v_and_b32_e32 v137, 0xffff0000, v46
	v_lshlrev_b32_e32 v138, 16, v47
	v_and_b32_e32 v139, 0xffff0000, v47
	v_pk_mul_f32 v[236:237], v[130:131], v[236:237] op_sel_hi:[0,1]
	v_pk_fma_f32 v[236:237], v[28:29], v[236:237], v[136:137]
	v_pk_mul_f32 v[238:239], v[130:131], v[238:239] op_sel_hi:[0,1]
	v_pk_fma_f32 v[238:239], v[30:31], v[238:239], v[138:139]
	global_store_dwordx4 v[140:141], v[236:239], off offset:3072
	v_lshl_add_u64 v[250:251], v[250:251], 0, s[12:13]
	global_load_dwordx2 v[144:145], v252, s[0:1] offset:0
	global_load_dwordx2 v[146:147], v252, s[0:1] offset:512
	global_load_dwordx2 v[148:149], v252, s[0:1] offset:1024
	global_load_dwordx2 v[150:151], v252, s[0:1] offset:1536
	global_load_dwordx2 v[152:153], v252, s[0:1] offset:2048
	global_load_dwordx2 v[154:155], v252, s[0:1] offset:2560
	global_load_dwordx2 v[156:157], v252, s[0:1] offset:3072
	global_load_dwordx2 v[158:159], v252, s[0:1] offset:3584
	global_load_dwordx2 v[160:161], v252, s[2:3] offset:0
	global_load_dwordx2 v[162:163], v252, s[2:3] offset:512
	global_load_dwordx2 v[164:165], v252, s[2:3] offset:1024
	global_load_dwordx2 v[166:167], v252, s[2:3] offset:1536
	global_load_dwordx2 v[168:169], v252, s[2:3] offset:2048
	global_load_dwordx2 v[170:171], v252, s[2:3] offset:2560
	global_load_dwordx2 v[172:173], v252, s[2:3] offset:3072
	global_load_dwordx2 v[174:175], v252, s[2:3] offset:3584
	s_add_u32 s0, s0, 0x8000
	s_addc_u32 s1, s1, 0
	s_add_u32 s2, s2, 0x8000
	s_addc_u32 s3, s3, 0
	s_waitcnt vmcnt(40)
	v_lshlrev_b32_e32 v208, 16, v80
	v_and_b32_e32 v209, 0xffff0000, v80
	v_lshlrev_b32_e32 v210, 16, v81
	v_and_b32_e32 v211, 0xffff0000, v81
	v_lshlrev_b32_e32 v212, 16, v82
	v_and_b32_e32 v213, 0xffff0000, v82
	v_lshlrev_b32_e32 v214, 16, v83
	v_and_b32_e32 v215, 0xffff0000, v83
	v_lshlrev_b32_e32 v216, 16, v84
	v_and_b32_e32 v217, 0xffff0000, v84
	v_lshlrev_b32_e32 v218, 16, v85
	v_and_b32_e32 v219, 0xffff0000, v85
	v_lshlrev_b32_e32 v220, 16, v86
	v_and_b32_e32 v221, 0xffff0000, v86
	v_lshlrev_b32_e32 v222, 16, v87
	v_and_b32_e32 v223, 0xffff0000, v87
	v_lshlrev_b32_e32 v224, 16, v88
	v_and_b32_e32 v225, 0xffff0000, v88
	v_lshlrev_b32_e32 v226, 16, v89
	v_and_b32_e32 v227, 0xffff0000, v89
	v_lshlrev_b32_e32 v228, 16, v90
	v_and_b32_e32 v229, 0xffff0000, v90
	v_lshlrev_b32_e32 v230, 16, v91
	v_and_b32_e32 v231, 0xffff0000, v91
	v_lshlrev_b32_e32 v232, 16, v92
	v_and_b32_e32 v233, 0xffff0000, v92
	v_lshlrev_b32_e32 v234, 16, v93
	v_and_b32_e32 v235, 0xffff0000, v93
	v_lshlrev_b32_e32 v236, 16, v94
	v_and_b32_e32 v237, 0xffff0000, v94
	v_lshlrev_b32_e32 v238, 16, v95
	v_and_b32_e32 v239, 0xffff0000, v95
	v_mul_f32_e32 v128, v208, v208
	v_fmac_f32_e32 v128, v209, v209
	v_mul_f32_e32 v129, v210, v210
	v_fmac_f32_e32 v129, v211, v211
	v_add_f32_e32 v128, v128, v129
	v_mul_f32_e32 v129, v212, v212
	v_fmac_f32_e32 v129, v213, v213
	v_mul_f32_e32 v132, v214, v214
	v_fmac_f32_e32 v132, v215, v215
	v_add_f32_e32 v129, v129, v132
	v_add_f32_e32 v128, v128, v129
	v_mul_f32_e32 v129, v216, v216
	v_fmac_f32_e32 v129, v217, v217
	v_mul_f32_e32 v132, v218, v218
	v_fmac_f32_e32 v132, v219, v219
	v_add_f32_e32 v129, v129, v132
	v_add_f32_e32 v128, v128, v129
	v_mul_f32_e32 v129, v220, v220
	v_fmac_f32_e32 v129, v221, v221
	v_mul_f32_e32 v132, v222, v222
	v_fmac_f32_e32 v132, v223, v223
	v_add_f32_e32 v129, v129, v132
	v_add_f32_e32 v128, v128, v129
	v_mul_f32_e32 v129, v224, v224
	v_fmac_f32_e32 v129, v225, v225
	v_mul_f32_e32 v132, v226, v226
	v_fmac_f32_e32 v132, v227, v227
	v_add_f32_e32 v129, v129, v132
	v_add_f32_e32 v128, v128, v129
	v_mul_f32_e32 v129, v228, v228
	v_fmac_f32_e32 v129, v229, v229
	v_mul_f32_e32 v132, v230, v230
	v_fmac_f32_e32 v132, v231, v231
	v_add_f32_e32 v129, v129, v132
	v_add_f32_e32 v128, v128, v129
	v_mul_f32_e32 v129, v232, v232
	v_fmac_f32_e32 v129, v233, v233
	v_mul_f32_e32 v132, v234, v234
	v_fmac_f32_e32 v132, v235, v235
	v_add_f32_e32 v129, v129, v132
	v_add_f32_e32 v128, v128, v129
	v_mul_f32_e32 v129, v236, v236
	v_fmac_f32_e32 v129, v237, v237
	v_mul_f32_e32 v132, v238, v238
	v_fmac_f32_e32 v132, v239, v239
	v_add_f32_e32 v129, v129, v132
	v_add_f32_e32 v128, v128, v129
	ds_bpermute_b32 v129, v244, v128
	s_waitcnt lgkmcnt(0)
	v_add_f32_e32 v128, v128, v129
	ds_bpermute_b32 v129, v245, v128
	s_waitcnt lgkmcnt(0)
	v_add_f32_e32 v128, v128, v129
	ds_bpermute_b32 v129, v246, v128
	s_waitcnt lgkmcnt(0)
	v_add_f32_e32 v128, v128, v129
	ds_bpermute_b32 v129, v247, v128
	s_waitcnt lgkmcnt(0)
	v_add_f32_e32 v128, v128, v129
	ds_bpermute_b32 v129, v248, v128
	s_waitcnt lgkmcnt(0)
	v_add_f32_e32 v128, v128, v129
	ds_bpermute_b32 v129, v249, v128
	s_waitcnt lgkmcnt(0)
	v_add_f32_e32 v128, v128, v129
	v_fmamk_f32 v128, v128, 0x3a000000, v255
	v_mul_f32_e32 v129, 0x4b800000, v128
	v_cmp_gt_f32_e32 vcc, s10, v128
	s_nop 1
	v_cndmask_b32_e32 v128, v128, v129, vcc
	v_rsq_f32_e32 v128, v128
	s_nop 0
	v_mul_f32_e32 v129, 0x45800000, v128
	v_cndmask_b32_e32 v130, v128, v129, vcc
	v_lshl_add_u64 v[140:141], v[250:251], 0, s[14:15]
	v_lshlrev_b32_e32 v136, 16, v64
	v_and_b32_e32 v137, 0xffff0000, v64
	v_lshlrev_b32_e32 v138, 16, v65
	v_and_b32_e32 v139, 0xffff0000, v65
	v_pk_mul_f32 v[208:209], v[130:131], v[208:209] op_sel_hi:[0,1]
	v_pk_fma_f32 v[208:209], v[0:1], v[208:209], v[136:137]
	v_pk_mul_f32 v[210:211], v[130:131], v[210:211] op_sel_hi:[0,1]
	v_pk_fma_f32 v[210:211], v[2:3], v[210:211], v[138:139]
	global_store_dwordx4 v[250:251], v[208:211], off offset:0
	v_lshlrev_b32_e32 v136, 16, v66
	v_and_b32_e32 v137, 0xffff0000, v66
	v_lshlrev_b32_e32 v138, 16, v67
	v_and_b32_e32 v139, 0xffff0000, v67
	v_pk_mul_f32 v[212:213], v[130:131], v[212:213] op_sel_hi:[0,1]
	v_pk_fma_f32 v[212:213], v[4:5], v[212:213], v[136:137]
	v_pk_mul_f32 v[214:215], v[130:131], v[214:215] op_sel_hi:[0,1]
	v_pk_fma_f32 v[214:215], v[6:7], v[214:215], v[138:139]
	global_store_dwordx4 v[250:251], v[212:215], off offset:1024
	v_lshlrev_b32_e32 v136, 16, v68
	v_and_b32_e32 v137, 0xffff0000, v68
	v_lshlrev_b32_e32 v138, 16, v69
	v_and_b32_e32 v139, 0xffff0000, v69
	v_pk_mul_f32 v[216:217], v[130:131], v[216:217] op_sel_hi:[0,1]
	v_pk_fma_f32 v[216:217], v[8:9], v[216:217], v[136:137]
	v_pk_mul_f32 v[218:219], v[130:131], v[218:219] op_sel_hi:[0,1]
	v_pk_fma_f32 v[218:219], v[10:11], v[218:219], v[138:139]
	global_store_dwordx4 v[250:251], v[216:219], off offset:2048
	v_lshlrev_b32_e32 v136, 16, v70
	v_and_b32_e32 v137, 0xffff0000, v70
	v_lshlrev_b32_e32 v138, 16, v71
	v_and_b32_e32 v139, 0xffff0000, v71
	v_pk_mul_f32 v[220:221], v[130:131], v[220:221] op_sel_hi:[0,1]
	v_pk_fma_f32 v[220:221], v[12:13], v[220:221], v[136:137]
	v_pk_mul_f32 v[222:223], v[130:131], v[222:223] op_sel_hi:[0,1]
	v_pk_fma_f32 v[222:223], v[14:15], v[222:223], v[138:139]
	global_store_dwordx4 v[250:251], v[220:223], off offset:3072
	v_lshlrev_b32_e32 v136, 16, v72
	v_and_b32_e32 v137, 0xffff0000, v72
	v_lshlrev_b32_e32 v138, 16, v73
	v_and_b32_e32 v139, 0xffff0000, v73
	v_pk_mul_f32 v[224:225], v[130:131], v[224:225] op_sel_hi:[0,1]
	v_pk_fma_f32 v[224:225], v[16:17], v[224:225], v[136:137]
	v_pk_mul_f32 v[226:227], v[130:131], v[226:227] op_sel_hi:[0,1]
	v_pk_fma_f32 v[226:227], v[18:19], v[226:227], v[138:139]
	global_store_dwordx4 v[140:141], v[224:227], off offset:0
	v_lshlrev_b32_e32 v136, 16, v74
	v_and_b32_e32 v137, 0xffff0000, v74
	v_lshlrev_b32_e32 v138, 16, v75
	v_and_b32_e32 v139, 0xffff0000, v75
	v_pk_mul_f32 v[228:229], v[130:131], v[228:229] op_sel_hi:[0,1]
	v_pk_fma_f32 v[228:229], v[20:21], v[228:229], v[136:137]
	v_pk_mul_f32 v[230:231], v[130:131], v[230:231] op_sel_hi:[0,1]
	v_pk_fma_f32 v[230:231], v[22:23], v[230:231], v[138:139]
	global_store_dwordx4 v[140:141], v[228:231], off offset:1024
	v_lshlrev_b32_e32 v136, 16, v76
	v_and_b32_e32 v137, 0xffff0000, v76
	v_lshlrev_b32_e32 v138, 16, v77
	v_and_b32_e32 v139, 0xffff0000, v77
	v_pk_mul_f32 v[232:233], v[130:131], v[232:233] op_sel_hi:[0,1]
	v_pk_fma_f32 v[232:233], v[24:25], v[232:233], v[136:137]
	v_pk_mul_f32 v[234:235], v[130:131], v[234:235] op_sel_hi:[0,1]
	v_pk_fma_f32 v[234:235], v[26:27], v[234:235], v[138:139]
	global_store_dwordx4 v[140:141], v[232:235], off offset:2048
	v_lshlrev_b32_e32 v136, 16, v78
	v_and_b32_e32 v137, 0xffff0000, v78
	v_lshlrev_b32_e32 v138, 16, v79
	v_and_b32_e32 v139, 0xffff0000, v79
	v_pk_mul_f32 v[236:237], v[130:131], v[236:237] op_sel_hi:[0,1]
	v_pk_fma_f32 v[236:237], v[28:29], v[236:237], v[136:137]
	v_pk_mul_f32 v[238:239], v[130:131], v[238:239] op_sel_hi:[0,1]
	v_pk_fma_f32 v[238:239], v[30:31], v[238:239], v[138:139]
	global_store_dwordx4 v[140:141], v[236:239], off offset:3072
	v_lshl_add_u64 v[250:251], v[250:251], 0, s[12:13]
	s_waitcnt vmcnt(32)
	s_cmpk_gt_i32 s11, 1
	s_cbranch_scc1 .Lp15_no5a
	global_load_dwordx2 v[176:177], v252, s[0:1] offset:0
	global_load_dwordx2 v[178:179], v252, s[0:1] offset:512
	global_load_dwordx2 v[180:181], v252, s[0:1] offset:1024
	global_load_dwordx2 v[182:183], v252, s[0:1] offset:1536
	global_load_dwordx2 v[184:185], v252, s[0:1] offset:2048
	global_load_dwordx2 v[186:187], v252, s[0:1] offset:2560
	global_load_dwordx2 v[188:189], v252, s[0:1] offset:3072
	global_load_dwordx2 v[190:191], v252, s[0:1] offset:3584
	global_load_dwordx2 v[192:193], v252, s[2:3] offset:0
	global_load_dwordx2 v[194:195], v252, s[2:3] offset:512
	global_load_dwordx2 v[196:197], v252, s[2:3] offset:1024
	global_load_dwordx2 v[198:199], v252, s[2:3] offset:1536
	global_load_dwordx2 v[200:201], v252, s[2:3] offset:2048
	global_load_dwordx2 v[202:203], v252, s[2:3] offset:2560
	global_load_dwordx2 v[204:205], v252, s[2:3] offset:3072
	global_load_dwordx2 v[206:207], v252, s[2:3] offset:3584
	s_add_u32 s0, s0, 0x8000
	s_addc_u32 s1, s1, 0
	s_add_u32 s2, s2, 0x8000
	s_addc_u32 s3, s3, 0
.Lp15_no5a:
	v_lshlrev_b32_e32 v208, 16, v112
	v_and_b32_e32 v209, 0xffff0000, v112
	v_lshlrev_b32_e32 v210, 16, v113
	v_and_b32_e32 v211, 0xffff0000, v113
	v_lshlrev_b32_e32 v212, 16, v114
	v_and_b32_e32 v213, 0xffff0000, v114
	v_lshlrev_b32_e32 v214, 16, v115
	v_and_b32_e32 v215, 0xffff0000, v115
	v_lshlrev_b32_e32 v216, 16, v116
	v_and_b32_e32 v217, 0xffff0000, v116
	v_lshlrev_b32_e32 v218, 16, v117
	v_and_b32_e32 v219, 0xffff0000, v117
	v_lshlrev_b32_e32 v220, 16, v118
	v_and_b32_e32 v221, 0xffff0000, v118
	v_lshlrev_b32_e32 v222, 16, v119
	v_and_b32_e32 v223, 0xffff0000, v119
	v_lshlrev_b32_e32 v224, 16, v120
	v_and_b32_e32 v225, 0xffff0000, v120
	v_lshlrev_b32_e32 v226, 16, v121
	v_and_b32_e32 v227, 0xffff0000, v121
	v_lshlrev_b32_e32 v228, 16, v122
	v_and_b32_e32 v229, 0xffff0000, v122
	v_lshlrev_b32_e32 v230, 16, v123
	v_and_b32_e32 v231, 0xffff0000, v123
	v_lshlrev_b32_e32 v232, 16, v124
	v_and_b32_e32 v233, 0xffff0000, v124
	v_lshlrev_b32_e32 v234, 16, v125
	v_and_b32_e32 v235, 0xffff0000, v125
	v_lshlrev_b32_e32 v236, 16, v126
	v_and_b32_e32 v237, 0xffff0000, v126
	v_lshlrev_b32_e32 v238, 16, v127
	v_and_b32_e32 v239, 0xffff0000, v127
	v_mul_f32_e32 v128, v208, v208
	v_fmac_f32_e32 v128, v209, v209
	v_mul_f32_e32 v129, v210, v210
	v_fmac_f32_e32 v129, v211, v211
	v_add_f32_e32 v128, v128, v129
	v_mul_f32_e32 v129, v212, v212
	v_fmac_f32_e32 v129, v213, v213
	v_mul_f32_e32 v132, v214, v214
	v_fmac_f32_e32 v132, v215, v215
	v_add_f32_e32 v129, v129, v132
	v_add_f32_e32 v128, v128, v129
	v_mul_f32_e32 v129, v216, v216
	v_fmac_f32_e32 v129, v217, v217
	v_mul_f32_e32 v132, v218, v218
	v_fmac_f32_e32 v132, v219, v219
	v_add_f32_e32 v129, v129, v132
	v_add_f32_e32 v128, v128, v129
	v_mul_f32_e32 v129, v220, v220
	v_fmac_f32_e32 v129, v221, v221
	v_mul_f32_e32 v132, v222, v222
	v_fmac_f32_e32 v132, v223, v223
	v_add_f32_e32 v129, v129, v132
	v_add_f32_e32 v128, v128, v129
	v_mul_f32_e32 v129, v224, v224
	v_fmac_f32_e32 v129, v225, v225
	v_mul_f32_e32 v132, v226, v226
	v_fmac_f32_e32 v132, v227, v227
	v_add_f32_e32 v129, v129, v132
	v_add_f32_e32 v128, v128, v129
	v_mul_f32_e32 v129, v228, v228
	v_fmac_f32_e32 v129, v229, v229
	v_mul_f32_e32 v132, v230, v230
	v_fmac_f32_e32 v132, v231, v231
	v_add_f32_e32 v129, v129, v132
	v_add_f32_e32 v128, v128, v129
	v_mul_f32_e32 v129, v232, v232
	v_fmac_f32_e32 v129, v233, v233
	v_mul_f32_e32 v132, v234, v234
	v_fmac_f32_e32 v132, v235, v235
	v_add_f32_e32 v129, v129, v132
	v_add_f32_e32 v128, v128, v129
	v_mul_f32_e32 v129, v236, v236
	v_fmac_f32_e32 v129, v237, v237
	v_mul_f32_e32 v132, v238, v238
	v_fmac_f32_e32 v132, v239, v239
	v_add_f32_e32 v129, v129, v132
	v_add_f32_e32 v128, v128, v129
	ds_bpermute_b32 v129, v244, v128
	s_waitcnt lgkmcnt(0)
	v_add_f32_e32 v128, v128, v129
	ds_bpermute_b32 v129, v245, v128
	s_waitcnt lgkmcnt(0)
	v_add_f32_e32 v128, v128, v129
	ds_bpermute_b32 v129, v246, v128
	s_waitcnt lgkmcnt(0)
	v_add_f32_e32 v128, v128, v129
	ds_bpermute_b32 v129, v247, v128
	s_waitcnt lgkmcnt(0)
	v_add_f32_e32 v128, v128, v129
	ds_bpermute_b32 v129, v248, v128
	s_waitcnt lgkmcnt(0)
	v_add_f32_e32 v128, v128, v129
	ds_bpermute_b32 v129, v249, v128
	s_waitcnt lgkmcnt(0)
	v_add_f32_e32 v128, v128, v129
	v_fmamk_f32 v128, v128, 0x3a000000, v255
	v_mul_f32_e32 v129, 0x4b800000, v128
	v_cmp_gt_f32_e32 vcc, s10, v128
	s_nop 1
	v_cndmask_b32_e32 v128, v128, v129, vcc
	v_rsq_f32_e32 v128, v128
	s_nop 0
	v_mul_f32_e32 v129, 0x45800000, v128
	v_cndmask_b32_e32 v130, v128, v129, vcc
	v_lshl_add_u64 v[140:141], v[250:251], 0, s[14:15]
	v_lshlrev_b32_e32 v136, 16, v96
	v_and_b32_e32 v137, 0xffff0000, v96
	v_lshlrev_b32_e32 v138, 16, v97
	v_and_b32_e32 v139, 0xffff0000, v97
	v_pk_mul_f32 v[208:209], v[130:131], v[208:209] op_sel_hi:[0,1]
	v_pk_fma_f32 v[208:209], v[0:1], v[208:209], v[136:137]
	v_pk_mul_f32 v[210:211], v[130:131], v[210:211] op_sel_hi:[0,1]
	v_pk_fma_f32 v[210:211], v[2:3], v[210:211], v[138:139]
	global_store_dwordx4 v[250:251], v[208:211], off offset:0
	v_lshlrev_b32_e32 v136, 16, v98
	v_and_b32_e32 v137, 0xffff0000, v98
	v_lshlrev_b32_e32 v138, 16, v99
	v_and_b32_e32 v139, 0xffff0000, v99
	v_pk_mul_f32 v[212:213], v[130:131], v[212:213] op_sel_hi:[0,1]
	v_pk_fma_f32 v[212:213], v[4:5], v[212:213], v[136:137]
	v_pk_mul_f32 v[214:215], v[130:131], v[214:215] op_sel_hi:[0,1]
	v_pk_fma_f32 v[214:215], v[6:7], v[214:215], v[138:139]
	global_store_dwordx4 v[250:251], v[212:215], off offset:1024
	v_lshlrev_b32_e32 v136, 16, v100
	v_and_b32_e32 v137, 0xffff0000, v100
	v_lshlrev_b32_e32 v138, 16, v101
	v_and_b32_e32 v139, 0xffff0000, v101
	v_pk_mul_f32 v[216:217], v[130:131], v[216:217] op_sel_hi:[0,1]
	v_pk_fma_f32 v[216:217], v[8:9], v[216:217], v[136:137]
	v_pk_mul_f32 v[218:219], v[130:131], v[218:219] op_sel_hi:[0,1]
	v_pk_fma_f32 v[218:219], v[10:11], v[218:219], v[138:139]
	global_store_dwordx4 v[250:251], v[216:219], off offset:2048
	v_lshlrev_b32_e32 v136, 16, v102
	v_and_b32_e32 v137, 0xffff0000, v102
	v_lshlrev_b32_e32 v138, 16, v103
	v_and_b32_e32 v139, 0xffff0000, v103
	v_pk_mul_f32 v[220:221], v[130:131], v[220:221] op_sel_hi:[0,1]
	v_pk_fma_f32 v[220:221], v[12:13], v[220:221], v[136:137]
	v_pk_mul_f32 v[222:223], v[130:131], v[222:223] op_sel_hi:[0,1]
	v_pk_fma_f32 v[222:223], v[14:15], v[222:223], v[138:139]
	global_store_dwordx4 v[250:251], v[220:223], off offset:3072
	v_lshlrev_b32_e32 v136, 16, v104
	v_and_b32_e32 v137, 0xffff0000, v104
	v_lshlrev_b32_e32 v138, 16, v105
	v_and_b32_e32 v139, 0xffff0000, v105
	v_pk_mul_f32 v[224:225], v[130:131], v[224:225] op_sel_hi:[0,1]
	v_pk_fma_f32 v[224:225], v[16:17], v[224:225], v[136:137]
	v_pk_mul_f32 v[226:227], v[130:131], v[226:227] op_sel_hi:[0,1]
	v_pk_fma_f32 v[226:227], v[18:19], v[226:227], v[138:139]
	global_store_dwordx4 v[140:141], v[224:227], off offset:0
	v_lshlrev_b32_e32 v136, 16, v106
	v_and_b32_e32 v137, 0xffff0000, v106
	v_lshlrev_b32_e32 v138, 16, v107
	v_and_b32_e32 v139, 0xffff0000, v107
	v_pk_mul_f32 v[228:229], v[130:131], v[228:229] op_sel_hi:[0,1]
	v_pk_fma_f32 v[228:229], v[20:21], v[228:229], v[136:137]
	v_pk_mul_f32 v[230:231], v[130:131], v[230:231] op_sel_hi:[0,1]
	v_pk_fma_f32 v[230:231], v[22:23], v[230:231], v[138:139]
	global_store_dwordx4 v[140:141], v[228:231], off offset:1024
	v_lshlrev_b32_e32 v136, 16, v108
	v_and_b32_e32 v137, 0xffff0000, v108
	v_lshlrev_b32_e32 v138, 16, v109
	v_and_b32_e32 v139, 0xffff0000, v109
	v_pk_mul_f32 v[232:233], v[130:131], v[232:233] op_sel_hi:[0,1]
	v_pk_fma_f32 v[232:233], v[24:25], v[232:233], v[136:137]
	v_pk_mul_f32 v[234:235], v[130:131], v[234:235] op_sel_hi:[0,1]
	v_pk_fma_f32 v[234:235], v[26:27], v[234:235], v[138:139]
	global_store_dwordx4 v[140:141], v[232:235], off offset:2048
	v_lshlrev_b32_e32 v136, 16, v110
	v_and_b32_e32 v137, 0xffff0000, v110
	v_lshlrev_b32_e32 v138, 16, v111
	v_and_b32_e32 v139, 0xffff0000, v111
	v_pk_mul_f32 v[236:237], v[130:131], v[236:237] op_sel_hi:[0,1]
	v_pk_fma_f32 v[236:237], v[28:29], v[236:237], v[136:137]
	v_pk_mul_f32 v[238:239], v[130:131], v[238:239] op_sel_hi:[0,1]
	v_pk_fma_f32 v[238:239], v[30:31], v[238:239], v[138:139]
	global_store_dwordx4 v[140:141], v[236:239], off offset:3072
	v_lshl_add_u64 v[250:251], v[250:251], 0, s[12:13]
	s_waitcnt vmcnt(16)
	v_lshlrev_b32_e32 v208, 16, v160
	v_and_b32_e32 v209, 0xffff0000, v160
	v_lshlrev_b32_e32 v210, 16, v161
	v_and_b32_e32 v211, 0xffff0000, v161
	v_lshlrev_b32_e32 v212, 16, v162
	v_and_b32_e32 v213, 0xffff0000, v162
	v_lshlrev_b32_e32 v214, 16, v163
	v_and_b32_e32 v215, 0xffff0000, v163
	v_lshlrev_b32_e32 v216, 16, v164
	v_and_b32_e32 v217, 0xffff0000, v164
	v_lshlrev_b32_e32 v218, 16, v165
	v_and_b32_e32 v219, 0xffff0000, v165
	v_lshlrev_b32_e32 v220, 16, v166
	v_and_b32_e32 v221, 0xffff0000, v166
	v_lshlrev_b32_e32 v222, 16, v167
	v_and_b32_e32 v223, 0xffff0000, v167
	v_lshlrev_b32_e32 v224, 16, v168
	v_and_b32_e32 v225, 0xffff0000, v168
	v_lshlrev_b32_e32 v226, 16, v169
	v_and_b32_e32 v227, 0xffff0000, v169
	v_lshlrev_b32_e32 v228, 16, v170
	v_and_b32_e32 v229, 0xffff0000, v170
	v_lshlrev_b32_e32 v230, 16, v171
	v_and_b32_e32 v231, 0xffff0000, v171
	v_lshlrev_b32_e32 v232, 16, v172
	v_and_b32_e32 v233, 0xffff0000, v172
	v_lshlrev_b32_e32 v234, 16, v173
	v_and_b32_e32 v235, 0xffff0000, v173
	v_lshlrev_b32_e32 v236, 16, v174
	v_and_b32_e32 v237, 0xffff0000, v174
	v_lshlrev_b32_e32 v238, 16, v175
	v_and_b32_e32 v239, 0xffff0000, v175
	v_mul_f32_e32 v128, v208, v208
	v_fmac_f32_e32 v128, v209, v209
	v_mul_f32_e32 v129, v210, v210
	v_fmac_f32_e32 v129, v211, v211
	v_add_f32_e32 v128, v128, v129
	v_mul_f32_e32 v129, v212, v212
	v_fmac_f32_e32 v129, v213, v213
	v_mul_f32_e32 v132, v214, v214
	v_fmac_f32_e32 v132, v215, v215
	v_add_f32_e32 v129, v129, v132
	v_add_f32_e32 v128, v128, v129
	v_mul_f32_e32 v129, v216, v216
	v_fmac_f32_e32 v129, v217, v217
	v_mul_f32_e32 v132, v218, v218
	v_fmac_f32_e32 v132, v219, v219
	v_add_f32_e32 v129, v129, v132
	v_add_f32_e32 v128, v128, v129
	v_mul_f32_e32 v129, v220, v220
	v_fmac_f32_e32 v129, v221, v221
	v_mul_f32_e32 v132, v222, v222
	v_fmac_f32_e32 v132, v223, v223
	v_add_f32_e32 v129, v129, v132
	v_add_f32_e32 v128, v128, v129
	v_mul_f32_e32 v129, v224, v224
	v_fmac_f32_e32 v129, v225, v225
	v_mul_f32_e32 v132, v226, v226
	v_fmac_f32_e32 v132, v227, v227
	v_add_f32_e32 v129, v129, v132
	v_add_f32_e32 v128, v128, v129
	v_mul_f32_e32 v129, v228, v228
	v_fmac_f32_e32 v129, v229, v229
	v_mul_f32_e32 v132, v230, v230
	v_fmac_f32_e32 v132, v231, v231
	v_add_f32_e32 v129, v129, v132
	v_add_f32_e32 v128, v128, v129
	v_mul_f32_e32 v129, v232, v232
	v_fmac_f32_e32 v129, v233, v233
	v_mul_f32_e32 v132, v234, v234
	v_fmac_f32_e32 v132, v235, v235
	v_add_f32_e32 v129, v129, v132
	v_add_f32_e32 v128, v128, v129
	v_mul_f32_e32 v129, v236, v236
	v_fmac_f32_e32 v129, v237, v237
	v_mul_f32_e32 v132, v238, v238
	v_fmac_f32_e32 v132, v239, v239
	v_add_f32_e32 v129, v129, v132
	v_add_f32_e32 v128, v128, v129
	ds_bpermute_b32 v129, v244, v128
	s_waitcnt lgkmcnt(0)
	v_add_f32_e32 v128, v128, v129
	ds_bpermute_b32 v129, v245, v128
	s_waitcnt lgkmcnt(0)
	v_add_f32_e32 v128, v128, v129
	ds_bpermute_b32 v129, v246, v128
	s_waitcnt lgkmcnt(0)
	v_add_f32_e32 v128, v128, v129
	ds_bpermute_b32 v129, v247, v128
	s_waitcnt lgkmcnt(0)
	v_add_f32_e32 v128, v128, v129
	ds_bpermute_b32 v129, v248, v128
	s_waitcnt lgkmcnt(0)
	v_add_f32_e32 v128, v128, v129
	ds_bpermute_b32 v129, v249, v128
	s_waitcnt lgkmcnt(0)
	v_add_f32_e32 v128, v128, v129
	v_fmamk_f32 v128, v128, 0x3a000000, v255
	v_mul_f32_e32 v129, 0x4b800000, v128
	v_cmp_gt_f32_e32 vcc, s10, v128
	s_nop 1
	v_cndmask_b32_e32 v128, v128, v129, vcc
	v_rsq_f32_e32 v128, v128
	s_nop 0
	v_mul_f32_e32 v129, 0x45800000, v128
	v_cndmask_b32_e32 v130, v128, v129, vcc
	v_lshl_add_u64 v[140:141], v[250:251], 0, s[14:15]
	v_lshlrev_b32_e32 v136, 16, v144
	v_and_b32_e32 v137, 0xffff0000, v144
	v_lshlrev_b32_e32 v138, 16, v145
	v_and_b32_e32 v139, 0xffff0000, v145
	v_pk_mul_f32 v[208:209], v[130:131], v[208:209] op_sel_hi:[0,1]
	v_pk_fma_f32 v[208:209], v[0:1], v[208:209], v[136:137]
	v_pk_mul_f32 v[210:211], v[130:131], v[210:211] op_sel_hi:[0,1]
	v_pk_fma_f32 v[210:211], v[2:3], v[210:211], v[138:139]
	global_store_dwordx4 v[250:251], v[208:211], off offset:0
	v_lshlrev_b32_e32 v136, 16, v146
	v_and_b32_e32 v137, 0xffff0000, v146
	v_lshlrev_b32_e32 v138, 16, v147
	v_and_b32_e32 v139, 0xffff0000, v147
	v_pk_mul_f32 v[212:213], v[130:131], v[212:213] op_sel_hi:[0,1]
	v_pk_fma_f32 v[212:213], v[4:5], v[212:213], v[136:137]
	v_pk_mul_f32 v[214:215], v[130:131], v[214:215] op_sel_hi:[0,1]
	v_pk_fma_f32 v[214:215], v[6:7], v[214:215], v[138:139]
	global_store_dwordx4 v[250:251], v[212:215], off offset:1024
	v_lshlrev_b32_e32 v136, 16, v148
	v_and_b32_e32 v137, 0xffff0000, v148
	v_lshlrev_b32_e32 v138, 16, v149
	v_and_b32_e32 v139, 0xffff0000, v149
	v_pk_mul_f32 v[216:217], v[130:131], v[216:217] op_sel_hi:[0,1]
	v_pk_fma_f32 v[216:217], v[8:9], v[216:217], v[136:137]
	v_pk_mul_f32 v[218:219], v[130:131], v[218:219] op_sel_hi:[0,1]
	v_pk_fma_f32 v[218:219], v[10:11], v[218:219], v[138:139]
	global_store_dwordx4 v[250:251], v[216:219], off offset:2048
	v_lshlrev_b32_e32 v136, 16, v150
	v_and_b32_e32 v137, 0xffff0000, v150
	v_lshlrev_b32_e32 v138, 16, v151
	v_and_b32_e32 v139, 0xffff0000, v151
	v_pk_mul_f32 v[220:221], v[130:131], v[220:221] op_sel_hi:[0,1]
	v_pk_fma_f32 v[220:221], v[12:13], v[220:221], v[136:137]
	v_pk_mul_f32 v[222:223], v[130:131], v[222:223] op_sel_hi:[0,1]
	v_pk_fma_f32 v[222:223], v[14:15], v[222:223], v[138:139]
	global_store_dwordx4 v[250:251], v[220:223], off offset:3072
	v_lshlrev_b32_e32 v136, 16, v152
	v_and_b32_e32 v137, 0xffff0000, v152
	v_lshlrev_b32_e32 v138, 16, v153
	v_and_b32_e32 v139, 0xffff0000, v153
	v_pk_mul_f32 v[224:225], v[130:131], v[224:225] op_sel_hi:[0,1]
	v_pk_fma_f32 v[224:225], v[16:17], v[224:225], v[136:137]
	v_pk_mul_f32 v[226:227], v[130:131], v[226:227] op_sel_hi:[0,1]
	v_pk_fma_f32 v[226:227], v[18:19], v[226:227], v[138:139]
	global_store_dwordx4 v[140:141], v[224:227], off offset:0
	v_lshlrev_b32_e32 v136, 16, v154
	v_and_b32_e32 v137, 0xffff0000, v154
	v_lshlrev_b32_e32 v138, 16, v155
	v_and_b32_e32 v139, 0xffff0000, v155
	v_pk_mul_f32 v[228:229], v[130:131], v[228:229] op_sel_hi:[0,1]
	v_pk_fma_f32 v[228:229], v[20:21], v[228:229], v[136:137]
	v_pk_mul_f32 v[230:231], v[130:131], v[230:231] op_sel_hi:[0,1]
	v_pk_fma_f32 v[230:231], v[22:23], v[230:231], v[138:139]
	global_store_dwordx4 v[140:141], v[228:231], off offset:1024
	v_lshlrev_b32_e32 v136, 16, v156
	v_and_b32_e32 v137, 0xffff0000, v156
	v_lshlrev_b32_e32 v138, 16, v157
	v_and_b32_e32 v139, 0xffff0000, v157
	v_pk_mul_f32 v[232:233], v[130:131], v[232:233] op_sel_hi:[0,1]
	v_pk_fma_f32 v[232:233], v[24:25], v[232:233], v[136:137]
	v_pk_mul_f32 v[234:235], v[130:131], v[234:235] op_sel_hi:[0,1]
	v_pk_fma_f32 v[234:235], v[26:27], v[234:235], v[138:139]
	global_store_dwordx4 v[140:141], v[232:235], off offset:2048
	v_lshlrev_b32_e32 v136, 16, v158
	v_and_b32_e32 v137, 0xffff0000, v158
	v_lshlrev_b32_e32 v138, 16, v159
	v_and_b32_e32 v139, 0xffff0000, v159
	v_pk_mul_f32 v[236:237], v[130:131], v[236:237] op_sel_hi:[0,1]
	v_pk_fma_f32 v[236:237], v[28:29], v[236:237], v[136:137]
	v_pk_mul_f32 v[238:239], v[130:131], v[238:239] op_sel_hi:[0,1]
	v_pk_fma_f32 v[238:239], v[30:31], v[238:239], v[138:139]
	global_store_dwordx4 v[140:141], v[236:239], off offset:3072
	v_lshl_add_u64 v[250:251], v[250:251], 0, s[12:13]
	s_cmpk_gt_i32 s11, 1
	s_cbranch_scc1 .LBB0_1608
	s_waitcnt vmcnt(16)
	v_lshlrev_b32_e32 v208, 16, v192
	v_and_b32_e32 v209, 0xffff0000, v192
	v_lshlrev_b32_e32 v210, 16, v193
	v_and_b32_e32 v211, 0xffff0000, v193
	v_lshlrev_b32_e32 v212, 16, v194
	v_and_b32_e32 v213, 0xffff0000, v194
	v_lshlrev_b32_e32 v214, 16, v195
	v_and_b32_e32 v215, 0xffff0000, v195
	v_lshlrev_b32_e32 v216, 16, v196
	v_and_b32_e32 v217, 0xffff0000, v196
	v_lshlrev_b32_e32 v218, 16, v197
	v_and_b32_e32 v219, 0xffff0000, v197
	v_lshlrev_b32_e32 v220, 16, v198
	v_and_b32_e32 v221, 0xffff0000, v198
	v_lshlrev_b32_e32 v222, 16, v199
	v_and_b32_e32 v223, 0xffff0000, v199
	v_lshlrev_b32_e32 v224, 16, v200
	v_and_b32_e32 v225, 0xffff0000, v200
	v_lshlrev_b32_e32 v226, 16, v201
	v_and_b32_e32 v227, 0xffff0000, v201
	v_lshlrev_b32_e32 v228, 16, v202
	v_and_b32_e32 v229, 0xffff0000, v202
	v_lshlrev_b32_e32 v230, 16, v203
	v_and_b32_e32 v231, 0xffff0000, v203
	v_lshlrev_b32_e32 v232, 16, v204
	v_and_b32_e32 v233, 0xffff0000, v204
	v_lshlrev_b32_e32 v234, 16, v205
	v_and_b32_e32 v235, 0xffff0000, v205
	v_lshlrev_b32_e32 v236, 16, v206
	v_and_b32_e32 v237, 0xffff0000, v206
	v_lshlrev_b32_e32 v238, 16, v207
	v_and_b32_e32 v239, 0xffff0000, v207
	v_mul_f32_e32 v128, v208, v208
	v_fmac_f32_e32 v128, v209, v209
	v_mul_f32_e32 v129, v210, v210
	v_fmac_f32_e32 v129, v211, v211
	v_add_f32_e32 v128, v128, v129
	v_mul_f32_e32 v129, v212, v212
	v_fmac_f32_e32 v129, v213, v213
	v_mul_f32_e32 v132, v214, v214
	v_fmac_f32_e32 v132, v215, v215
	v_add_f32_e32 v129, v129, v132
	v_add_f32_e32 v128, v128, v129
	v_mul_f32_e32 v129, v216, v216
	v_fmac_f32_e32 v129, v217, v217
	v_mul_f32_e32 v132, v218, v218
	v_fmac_f32_e32 v132, v219, v219
	v_add_f32_e32 v129, v129, v132
	v_add_f32_e32 v128, v128, v129
	v_mul_f32_e32 v129, v220, v220
	v_fmac_f32_e32 v129, v221, v221
	v_mul_f32_e32 v132, v222, v222
	v_fmac_f32_e32 v132, v223, v223
	v_add_f32_e32 v129, v129, v132
	v_add_f32_e32 v128, v128, v129
	v_mul_f32_e32 v129, v224, v224
	v_fmac_f32_e32 v129, v225, v225
	v_mul_f32_e32 v132, v226, v226
	v_fmac_f32_e32 v132, v227, v227
	v_add_f32_e32 v129, v129, v132
	v_add_f32_e32 v128, v128, v129
	v_mul_f32_e32 v129, v228, v228
	v_fmac_f32_e32 v129, v229, v229
	v_mul_f32_e32 v132, v230, v230
	v_fmac_f32_e32 v132, v231, v231
	v_add_f32_e32 v129, v129, v132
	v_add_f32_e32 v128, v128, v129
	v_mul_f32_e32 v129, v232, v232
	v_fmac_f32_e32 v129, v233, v233
	v_mul_f32_e32 v132, v234, v234
	v_fmac_f32_e32 v132, v235, v235
	v_add_f32_e32 v129, v129, v132
	v_add_f32_e32 v128, v128, v129
	v_mul_f32_e32 v129, v236, v236
	v_fmac_f32_e32 v129, v237, v237
	v_mul_f32_e32 v132, v238, v238
	v_fmac_f32_e32 v132, v239, v239
	v_add_f32_e32 v129, v129, v132
	v_add_f32_e32 v128, v128, v129
	ds_bpermute_b32 v129, v244, v128
	s_waitcnt lgkmcnt(0)
	v_add_f32_e32 v128, v128, v129
	ds_bpermute_b32 v129, v245, v128
	s_waitcnt lgkmcnt(0)
	v_add_f32_e32 v128, v128, v129
	ds_bpermute_b32 v129, v246, v128
	s_waitcnt lgkmcnt(0)
	v_add_f32_e32 v128, v128, v129
	ds_bpermute_b32 v129, v247, v128
	s_waitcnt lgkmcnt(0)
	v_add_f32_e32 v128, v128, v129
	ds_bpermute_b32 v129, v248, v128
	s_waitcnt lgkmcnt(0)
	v_add_f32_e32 v128, v128, v129
	ds_bpermute_b32 v129, v249, v128
	s_waitcnt lgkmcnt(0)
	v_add_f32_e32 v128, v128, v129
	v_fmamk_f32 v128, v128, 0x3a000000, v255
	v_mul_f32_e32 v129, 0x4b800000, v128
	v_cmp_gt_f32_e32 vcc, s10, v128
	s_nop 1
	v_cndmask_b32_e32 v128, v128, v129, vcc
	v_rsq_f32_e32 v128, v128
	s_nop 0
	v_mul_f32_e32 v129, 0x45800000, v128
	v_cndmask_b32_e32 v130, v128, v129, vcc
	v_lshl_add_u64 v[140:141], v[250:251], 0, s[14:15]
	v_lshlrev_b32_e32 v136, 16, v176
	v_and_b32_e32 v137, 0xffff0000, v176
	v_lshlrev_b32_e32 v138, 16, v177
	v_and_b32_e32 v139, 0xffff0000, v177
	v_pk_mul_f32 v[208:209], v[130:131], v[208:209] op_sel_hi:[0,1]
	v_pk_fma_f32 v[208:209], v[0:1], v[208:209], v[136:137]
	v_pk_mul_f32 v[210:211], v[130:131], v[210:211] op_sel_hi:[0,1]
	v_pk_fma_f32 v[210:211], v[2:3], v[210:211], v[138:139]
	global_store_dwordx4 v[250:251], v[208:211], off offset:0
	v_lshlrev_b32_e32 v136, 16, v178
	v_and_b32_e32 v137, 0xffff0000, v178
	v_lshlrev_b32_e32 v138, 16, v179
	v_and_b32_e32 v139, 0xffff0000, v179
	v_pk_mul_f32 v[212:213], v[130:131], v[212:213] op_sel_hi:[0,1]
	v_pk_fma_f32 v[212:213], v[4:5], v[212:213], v[136:137]
	v_pk_mul_f32 v[214:215], v[130:131], v[214:215] op_sel_hi:[0,1]
	v_pk_fma_f32 v[214:215], v[6:7], v[214:215], v[138:139]
	global_store_dwordx4 v[250:251], v[212:215], off offset:1024
	v_lshlrev_b32_e32 v136, 16, v180
	v_and_b32_e32 v137, 0xffff0000, v180
	v_lshlrev_b32_e32 v138, 16, v181
	v_and_b32_e32 v139, 0xffff0000, v181
	v_pk_mul_f32 v[216:217], v[130:131], v[216:217] op_sel_hi:[0,1]
	v_pk_fma_f32 v[216:217], v[8:9], v[216:217], v[136:137]
	v_pk_mul_f32 v[218:219], v[130:131], v[218:219] op_sel_hi:[0,1]
	v_pk_fma_f32 v[218:219], v[10:11], v[218:219], v[138:139]
	global_store_dwordx4 v[250:251], v[216:219], off offset:2048
	v_lshlrev_b32_e32 v136, 16, v182
	v_and_b32_e32 v137, 0xffff0000, v182
	v_lshlrev_b32_e32 v138, 16, v183
	v_and_b32_e32 v139, 0xffff0000, v183
	v_pk_mul_f32 v[220:221], v[130:131], v[220:221] op_sel_hi:[0,1]
	v_pk_fma_f32 v[220:221], v[12:13], v[220:221], v[136:137]
	v_pk_mul_f32 v[222:223], v[130:131], v[222:223] op_sel_hi:[0,1]
	v_pk_fma_f32 v[222:223], v[14:15], v[222:223], v[138:139]
	global_store_dwordx4 v[250:251], v[220:223], off offset:3072
	v_lshlrev_b32_e32 v136, 16, v184
	v_and_b32_e32 v137, 0xffff0000, v184
	v_lshlrev_b32_e32 v138, 16, v185
	v_and_b32_e32 v139, 0xffff0000, v185
	v_pk_mul_f32 v[224:225], v[130:131], v[224:225] op_sel_hi:[0,1]
	v_pk_fma_f32 v[224:225], v[16:17], v[224:225], v[136:137]
	v_pk_mul_f32 v[226:227], v[130:131], v[226:227] op_sel_hi:[0,1]
	v_pk_fma_f32 v[226:227], v[18:19], v[226:227], v[138:139]
	global_store_dwordx4 v[140:141], v[224:227], off offset:0
	v_lshlrev_b32_e32 v136, 16, v186
	v_and_b32_e32 v137, 0xffff0000, v186
	v_lshlrev_b32_e32 v138, 16, v187
	v_and_b32_e32 v139, 0xffff0000, v187
	v_pk_mul_f32 v[228:229], v[130:131], v[228:229] op_sel_hi:[0,1]
	v_pk_fma_f32 v[228:229], v[20:21], v[228:229], v[136:137]
	v_pk_mul_f32 v[230:231], v[130:131], v[230:231] op_sel_hi:[0,1]
	v_pk_fma_f32 v[230:231], v[22:23], v[230:231], v[138:139]
	global_store_dwordx4 v[140:141], v[228:231], off offset:1024
	v_lshlrev_b32_e32 v136, 16, v188
	v_and_b32_e32 v137, 0xffff0000, v188
	v_lshlrev_b32_e32 v138, 16, v189
	v_and_b32_e32 v139, 0xffff0000, v189
	v_pk_mul_f32 v[232:233], v[130:131], v[232:233] op_sel_hi:[0,1]
	v_pk_fma_f32 v[232:233], v[24:25], v[232:233], v[136:137]
	v_pk_mul_f32 v[234:235], v[130:131], v[234:235] op_sel_hi:[0,1]
	v_pk_fma_f32 v[234:235], v[26:27], v[234:235], v[138:139]
	global_store_dwordx4 v[140:141], v[232:235], off offset:2048
	v_lshlrev_b32_e32 v136, 16, v190
	v_and_b32_e32 v137, 0xffff0000, v190
	v_lshlrev_b32_e32 v138, 16, v191
	v_and_b32_e32 v139, 0xffff0000, v191
	v_pk_mul_f32 v[236:237], v[130:131], v[236:237] op_sel_hi:[0,1]
	v_pk_fma_f32 v[236:237], v[28:29], v[236:237], v[136:137]
	v_pk_mul_f32 v[238:239], v[130:131], v[238:239] op_sel_hi:[0,1]
	v_pk_fma_f32 v[238:239], v[30:31], v[238:239], v[138:139]
	global_store_dwordx4 v[140:141], v[236:239], off offset:3072
	v_lshl_add_u64 v[250:251], v[250:251], 0, s[12:13]
